# transposes schedule variant: lighter in-proj tail and scan-phase shares, w_in[1] in FFN-up tail
# speedup vs baseline: 1.0458x; 1.0030x over previous
; __device__ __forceinline__ int bid_() { int t = blockIdx.x; asm volatile("" : "+s"(t)); return t; }
; __device__ __forceinline__ void prologue_phase(const Params& P, float* L) {
;     ...
;     bf16* W13 = (bf16*)(ws + WS_W13); bf16* W2 = (bf16*)(ws + WS_W2); bf16* WIN = (bf16*)(ws + WS_WIN); bf16* WOUT = (bf16*)(ws + WS_WOUT);
;     float* scr = L + wave * (64 * 65);
;     const int gw = bid_() * 8 + wave, NGW = gridDim.x * 8;
;     constexpr int I_F = 2816, I_LF = 3 * I_F, I_FFN = 4 * I_LF, I_IN = 32 * 101, I_OUT = 32 * 32, I_ALL = I_FFN + 2 * I_IN + 2 * I_OUT;
;     for (int it = gw; it < I_ALL; it += NGW) {
.LBB0_379:
	s_lshl_b32 s18, s2, 3
	v_readfirstlane_b32 s0, v168
	s_lshr_b32 s0, s0, 6
	s_add_u32 s18, s18, s0
	s_load_dword s20, s[38:39], 0x0
	s_mov_b32 s19, 6552
	s_mov_b32 s98, 5632
	s_mov_b32 s99, 0
	s_mov_b32 s100, 0xb00
	s_waitcnt lgkmcnt(0)
	s_lshl_b32 s20, s20, 3

; __device__ __forceinline__ void prologue_phase(const Params& P, float* L) {
;     ...
;     constexpr int I_F = 2816, I_LF = 3 * I_F, I_FFN = 4 * I_LF, I_IN = 32 * 101, I_OUT = 32 * 32, I_ALL = I_FFN + 2 * I_IN + 2 * I_OUT;
;     for (int it = gw; it < I_ALL; it += NGW) {
;         int r = it;
;         if (r < I_FFN) {
;             const int lf = r / I_LF, q = r % I_LF, which = q / I_F, item = q % I_F;
;             if (which == 0) transpose_item64(P.ffn_w1 + (size_t)lf * DM * FF, DM, FF, W13 + (size_t)lf * NUP * DM, 1, scr, item, lane);
;             else if (which == 1) transpose_item64(P.ffn_w3 + (size_t)lf * DM * FF, DM, FF, W13 + (size_t)lf * NUP * DM, 2, scr, item, lane);
;             else transpose_item64(P.ffn_w2 + (size_t)lf * FF * DM, FF, DM, W2 + (size_t)lf * DM * FF, 0, scr, item, lane);
;         } else {
;             r -= I_FFN;
;             if (r < 2 * I_IN) { const int l = r / I_IN, item = r % I_IN; transpose_item64(P.w_in + (size_t)l * DM * NIN, DM, NIN, WIN + (size_t)l * NINP_W * DM, 3, scr, item, lane); }
;             else { r -= 2 * I_IN; const int l = r / I_OUT, item = r % I_OUT; transpose_item64(P.w_out + (size_t)l * DM * DM, DM, DM, WOUT + (size_t)l * DM * DM, 0, scr, item, lane); }
;         }
.Lhk_n0:
	s_cmp_eq_u32 s36, 5
	s_cbranch_scc0 .Lhk_n1
	s_cmp_ge_u32 s2, 168
	s_cbranch_scc0 .Lhk_n1
	s_cmp_lt_u32 s2, 256
	s_cbranch_scc0 .Lhk_n1
	s_mov_b32 s0, 168
	s_mov_b32 s1, 88
	s_mov_b32 s99, 40256
	s_mov_b32 s98, 1024
	s_mov_b32 s100, 0x2098
	s_mov_b32 s19, 5000
	s_branch .Lhk_go
.Lhk_n1:
	s_cmp_eq_u32 s36, 7
	s_cbranch_scc0 .Lhk_n2
	s_cmp_ge_u32 s2, 192
	s_cbranch_scc0 .Lhk_n2
	s_cmp_lt_u32 s2, 224
	s_cbranch_scc0 .Lhk_n2
	s_mov_b32 s0, 192
	s_mov_b32 s1, 32
	s_mov_b32 s99, 13344
	s_mov_b32 s98, 4000
	s_mov_b32 s100, 0xfffff060
	s_mov_b32 s19, 4000
	s_branch .Lhk_go
.Lhk_n2:
	s_cmp_eq_u32 s36, 7
	s_cbranch_scc0 .Lhk_n3
	s_cmp_ge_u32 s2, 224
	s_cbranch_scc0 .Lhk_n3
	s_cmp_lt_u32 s2, 256
	s_cbranch_scc0 .Lhk_n3
	s_mov_b32 s0, 224
	s_mov_b32 s1, 32
	s_mov_b32 s99, 17344
	s_mov_b32 s98, 8000
	s_mov_b32 s100, 0xffffe0c0
	s_mov_b32 s19, 8000
	s_branch .Lhk_go
.Lhk_n3:
	s_cmp_eq_u32 s36, 14
	s_cbranch_scc0 .Lhk_n4
	s_cmp_ge_u32 s2, 48
	s_cbranch_scc0 .Lhk_n4
	s_cmp_lt_u32 s2, 256
	s_cbranch_scc0 .Lhk_n4
	s_mov_b32 s0, 48
	s_mov_b32 s1, 208
	s_mov_b32 s99, 37024
	s_mov_b32 s98, 3232
	s_mov_b32 s100, 0xfffff360
	s_mov_b32 s19, 3232
	s_branch .Lhk_go
